# attention block prologue v2: first K/V tile LDS-DMA issued before the Q-load wait (replaces the previous prologue edit); on top of v47
# speedup vs baseline: 1.0087x; 1.0068x over previous
.LBB0_613:
	s_and_b64 s[0:1], s[88:89], exec
	v_readlane_b32 s0, v252, 21
	v_readlane_b32 s1, v252, 25
	s_cselect_b32 s92, s0, s1
	v_readlane_b32 s0, v252, 13
	v_readlane_b32 s1, v252, 14
	s_add_i32 s82, s92, s0
	v_readlane_b32 s0, v252, 62
	v_readlane_b32 s1, v252, 63
	s_or_b32 s74, s92, s78
	s_lshr_b32 s81, s92, 6
	s_and_b64 vcc, exec, s[0:1]
	s_mov_b64 s[2:3], -1
	s_cbranch_vccz .LBB0_796
	v_mbcnt_lo_u32_b32 v190, -1, 0
	v_mbcnt_hi_u32_b32 v190, -1, v190
	v_readlane_b32 s0, v252, 17
	v_and_b32_e32 v189, 63, v190
	s_waitcnt vmcnt(0)
	v_lshlrev_b32_e32 v42, 4, v189
	v_or_b32_e32 v0, s0, v42
	s_mov_b32 s0, 0x51eb851f
	v_mul_hi_i32 v2, v0, s0
	v_lshrrev_b32_e32 v3, 31, v2
	v_ashrrev_i32_e32 v2, 7, v2
	v_add_u32_e32 v2, v2, v3
	v_and_b32_e32 v35, 63, v2
	v_mul_i32_i24_e32 v2, 0x190, v2
	v_sub_u32_e32 v2, v0, v2
	s_movk_i32 s1, 0x180
	v_ashrrev_i32_e32 v3, 4, v2
	v_cmp_gt_i32_e32 vcc, s1, v2
	v_readlane_b32 s2, v251, 49
	v_lshlrev_b32_e32 v43, 3, v189
	v_cndmask_b32_e32 v2, 0, v3, vcc
	v_cmp_lt_i32_e32 vcc, 15, v2
	v_mov_b32_e32 v4, s2
	v_or_b32_e32 v3, s78, v35
	v_cndmask_b32_e32 v5, v4, v181, vcc
	v_cndmask_b32_e64 v198, 12, 7, vcc
	v_lshl_add_u32 v200, v2, 4, v5
	v_add_u32_e32 v2, 0x2000, v0
	v_lshl_add_u32 v11, v3, v198, v200
	v_mul_hi_i32 v3, v2, s0
	v_lshrrev_b32_e32 v5, 31, v3
	v_ashrrev_i32_e32 v3, 7, v3
	v_add_u32_e32 v3, v3, v5
	v_and_b32_e32 v36, 63, v3
	v_mul_i32_i24_e32 v3, 0x190, v3
	v_sub_u32_e32 v2, v2, v3
	v_cndmask_b32_e32 v10, v248, v236, vcc
	v_ashrrev_i32_e32 v3, 4, v2
	v_cmp_gt_i32_e32 vcc, s1, v2
	v_add_u32_e32 v0, 0x4000, v0
	v_and_b32_e32 v39, 32, v190
	v_cndmask_b32_e32 v2, 0, v3, vcc
	v_cmp_lt_i32_e32 vcc, 15, v2
	v_and_b32_e32 v40, 24, v43
	v_bfe_u32 v191, v190, 5, 1
	v_cndmask_b32_e32 v3, v4, v181, vcc
	v_lshl_add_u32 v202, v2, 4, v3
	v_mul_hi_i32 v2, v0, s0
	v_lshrrev_b32_e32 v3, 31, v2
	v_ashrrev_i32_e32 v2, 7, v2
	v_add_u32_e32 v2, v2, v3
	v_and_b32_e32 v37, 63, v2
	v_mul_i32_i24_e32 v2, 0x190, v2
	v_sub_u32_e32 v0, v0, v2
	v_cndmask_b32_e64 v201, 12, 7, vcc
	v_cndmask_b32_e32 v12, v248, v236, vcc
	v_ashrrev_i32_e32 v2, 4, v0
	v_cmp_gt_i32_e32 vcc, s1, v0
	v_readlane_b32 s0, v250, 63
	v_and_b32_e32 v192, 31, v190
	v_cndmask_b32_e32 v0, 0, v2, vcc
	v_cmp_lt_i32_e32 vcc, 15, v0
	v_lshlrev_b32_e32 v34, 2, v191
	v_or_b32_e32 v5, s78, v36
	v_cndmask_b32_e32 v2, v4, v181, vcc
	v_lshl_add_u32 v204, v0, 4, v2
	v_add_u32_e32 v0, s0, v190
	v_bfe_u32 v38, v0, 2, 2
	v_lshrrev_b32_e32 v0, 1, v0
	v_and_b32_e32 v41, 8, v0
	v_readlane_b32 s0, v252, 1
	v_cndmask_b32_e64 v203, 12, 7, vcc
	v_or_b32_e32 v3, s78, v37
	v_or3_b32 v0, v38, s0, v41
	v_lshl_or_b32 v0, v0, 11, v39
	v_or3_b32 v0, v0, s72, v40
	v_or_b32_e32 v2, s82, v192
	v_lshlrev_b32_e32 v16, 1, v0
	v_lshl_add_u32 v13, v5, v201, v202
	v_cndmask_b32_e32 v14, v248, v236, vcc
	v_lshl_add_u32 v15, v3, v203, v204
	v_sub_u32_e32 v196, v2, v34
	v_add_u32_e32 v17, 0x1f700000, v16
	v_add_u32_e32 v18, 0x1f700080, v16
	v_add_u32_e32 v188, s70, v42
	s_setprio 1
	s_ashr_i32 s75, s74, 31
	s_lshl_b64 s[76:77], s[74:75], 12
	v_readlane_b32 s0, v252, 28
	v_readlane_b32 s2, v252, 13
	s_add_u32 s0, s0, s76
	v_readlane_b32 s1, v252, 31
	v_or_b32_e32 v0, s2, v192
	s_addc_u32 s1, s1, s77
	v_lshlrev_b64 v[2:3], 12, v[0:1]
	v_readlane_b32 s3, v252, 14
	v_lshl_add_u64 v[2:3], s[0:1], 0, v[2:3]
	s_lshl_b64 s[0:1], s[74:75], 11
	v_readlane_b32 s2, v252, 34
	v_lshlrev_b32_e32 v6, 4, v191
	v_mov_b32_e32 v7, v1
	s_add_u32 s2, s2, s0
	v_readlane_b32 s3, v252, 37
	v_lshl_add_u64 v[2:3], v[2:3], 0, v[6:7]
	v_lshlrev_b64 v[8:9], 11, v[0:1]
	s_addc_u32 s3, s3, s1
	flat_load_dwordx4 v[172:175], v[2:3]
	flat_load_dwordx4 v[168:171], v[2:3] offset:32
	flat_load_dwordx4 v[164:167], v[2:3] offset:64
	flat_load_dwordx4 v[160:163], v[2:3] offset:96
	flat_load_dwordx4 v[156:159], v[2:3] offset:128
	flat_load_dwordx4 v[152:155], v[2:3] offset:160
	flat_load_dwordx4 v[148:151], v[2:3] offset:192
	flat_load_dwordx4 v[144:147], v[2:3] offset:224
	v_lshl_add_u64 v[2:3], s[2:3], 0, v[8:9]
	v_lshl_add_u64 v[2:3], v[2:3], 0, v[6:7]
	flat_load_dwordx4 v[2:5], v[2:3]
	v_readlane_b32 s2, v252, 40
	s_add_u32 s0, s2, s0
	v_readlane_b32 s2, v252, 43
	s_addc_u32 s1, s2, s1
	v_add_u32_e32 v0, v11, v10
	s_cmp_lg_u32 0, -1
	v_lshl_add_u64 v[20:21], s[0:1], 0, v[8:9]
	v_lshl_add_u64 v[20:21], v[20:21], 0, v[6:7]
	s_mov_b32 s0, 0x29900000
	v_add_co_u32_e32 v8, vcc, s0, v20
	v_readlane_b32 s0, v250, 45
	s_nop 0
	v_addc_co_u32_e32 v9, vcc, 0, v21, vcc
	flat_load_dwordx4 v[24:27], v[8:9] offset:32
	flat_load_dwordx4 v[28:31], v[8:9] offset:64
	flat_load_dwordx4 v[44:47], v[8:9] offset:96
	s_mov_b32 m0, s0
	s_nop 0
	global_load_lds_dwordx4 v11, s[68:69]
	v_readlane_b32 s0, v251, 43
	s_mov_b32 m0, s0
	s_nop 0
	global_load_lds_dwordx4 v13, s[68:69]
	v_readlane_b32 s0, v253, 4
	s_mov_b32 m0, s33
	s_nop 0
	global_load_lds_dwordx4 v15, s[68:69]
	s_nop 0
	s_mov_b32 m0, s85
	s_nop 0
	global_load_lds_dwordx4 v17, s[68:69]
	s_nop 0
	s_mov_b32 m0, s0
	s_nop 0
	global_load_lds_dwordx4 v18, s[68:69]
	s_waitcnt vmcnt(0) lgkmcnt(0)
	ds_write_b128 v188, v[2:5]
	ds_write_b128 v188, v[24:27] offset:1024
	ds_write_b128 v188, v[28:31] offset:2048
	ds_write_b128 v188, v[44:47] offset:3072
	v_readlane_b32 s0, v251, 45
	s_waitcnt vmcnt(2)
	s_waitcnt lgkmcnt(0)
	s_barrier
	s_mov_b32 m0, s0
	s_nop 0
	global_load_lds_dwordx4 v0, s[68:69]
	v_readlane_b32 s0, v252, 9
	v_add_u32_e32 v0, v13, v12
	s_mov_b32 m0, s0
	s_nop 0
	global_load_lds_dwordx4 v0, s[68:69]
	v_readlane_b32 s0, v251, 47
	v_add_u32_e32 v0, v15, v14
	s_mov_b32 m0, s0
	s_nop 0
	global_load_lds_dwordx4 v0, s[68:69]
	v_readlane_b32 s0, v253, 7
	v_add_u32_e32 v0, 0x1f740000, v16
	s_mov_b32 m0, s0
	s_nop 0
	global_load_lds_dwordx4 v0, s[68:69]
	v_readlane_b32 s0, v253, 10
	v_add_u32_e32 v0, 0x1f740080, v16
	s_mov_b32 m0, s0
	s_nop 0
	global_load_lds_dwordx4 v0, s[68:69]
	s_cselect_b32 s0, 0, 0
	v_mul_u32_u24_e32 v0, 0x190, v192
	s_add_i32 s0, s0, 0xc000
	v_add3_u32 v205, v0, s0, v6
	ds_read_b128 v[2:5], v205 offset:0
	ds_read_b128 v[6:9], v205 offset:0x3200
	ds_read_b128 v[44:47], v205 offset:32
	ds_read_b128 v[48:51], v205 offset:0x3220
	ds_read_b128 v[52:55], v205 offset:64
	ds_read_b128 v[56:59], v205 offset:0x3240
	ds_read_b128 v[60:63], v205 offset:0x60
	ds_read_b128 v[64:67], v205 offset:0x3260
	s_nop 0
	s_waitcnt lgkmcnt(6)
	ds_read_b128 v[68:71], v205 offset:0x80
	ds_read_b128 v[72:75], v205 offset:0x3280
	s_waitcnt lgkmcnt(6)
	s_cmp_gt_u32 s82, 62
	v_mfma_f32_32x32x16_bf16 v[18:33], v[2:5], v[172:175], 0
	v_mfma_f32_32x32x16_bf16 v[2:17], v[6:9], v[172:175], 0
	v_mfma_f32_32x32x16_bf16 v[18:33], v[44:47], v[168:171], v[18:33]
	ds_read_b128 v[44:47], v205 offset:0xa0
	v_mfma_f32_32x32x16_bf16 v[2:17], v[48:51], v[168:171], v[2:17]
	ds_read_b128 v[48:51], v205 offset:0x32a0
	s_waitcnt lgkmcnt(6)
	s_nop 0
	v_mfma_f32_32x32x16_bf16 v[18:33], v[52:55], v[164:167], v[18:33]
	ds_read_b128 v[52:55], v205 offset:0xc0
	v_mfma_f32_32x32x16_bf16 v[2:17], v[56:59], v[164:167], v[2:17]
	ds_read_b128 v[56:59], v205 offset:0x32c0
	s_waitcnt lgkmcnt(6)
	s_nop 0
	v_mfma_f32_32x32x16_bf16 v[18:33], v[60:63], v[160:163], v[18:33]
	ds_read_b128 v[60:63], v205 offset:0xe0
	v_mfma_f32_32x32x16_bf16 v[2:17], v[64:67], v[160:163], v[2:17]
	ds_read_b128 v[64:67], v205 offset:0x32e0
	s_waitcnt lgkmcnt(6)
	s_nop 0
	v_mfma_f32_32x32x16_bf16 v[18:33], v[68:71], v[156:159], v[18:33]
	ds_read_b128 v[68:71], v205 offset:0x100
	v_mfma_f32_32x32x16_bf16 v[2:17], v[72:75], v[156:159], v[2:17]
	ds_read_b128 v[72:75], v205 offset:0x3300
	ds_read_b128 v[76:79], v188 offset:0
	s_waitcnt lgkmcnt(7)
	s_nop 0
	v_mfma_f32_32x32x16_bf16 v[18:33], v[44:47], v[152:155], v[18:33]
	ds_read_b128 v[44:47], v205 offset:0x120
	v_mfma_f32_32x32x16_bf16 v[2:17], v[48:51], v[152:155], v[2:17]
	ds_read_b128 v[48:51], v205 offset:0x3320
	ds_read_b128 v[80:83], v188 offset:0x400
	s_waitcnt lgkmcnt(8)
	s_nop 0
	v_mfma_f32_32x32x16_bf16 v[18:33], v[52:55], v[148:151], v[18:33]
	ds_read_b128 v[52:55], v205 offset:0x140
	v_mfma_f32_32x32x16_bf16 v[2:17], v[56:59], v[148:151], v[2:17]
	ds_read_b128 v[56:59], v205 offset:0x3340
	ds_read_b128 v[84:87], v188 offset:0x800
	s_waitcnt lgkmcnt(9)
	s_nop 0
	v_mfma_f32_32x32x16_bf16 v[18:33], v[60:63], v[144:147], v[18:33]
	ds_read_b128 v[60:63], v205 offset:0x160
	v_mfma_f32_32x32x16_bf16 v[2:17], v[64:67], v[144:147], v[2:17]
	ds_read_b128 v[64:67], v205 offset:0x3360
	ds_read_b128 v[88:91], v188 offset:0xc00
	s_waitcnt lgkmcnt(9)
	s_waitcnt lgkmcnt(6)
	s_waitcnt lgkmcnt(3)
	s_nop 0
	s_waitcnt lgkmcnt(0)
	v_mfma_f32_32x32x16_bf16 v[18:33], v[68:71], v[76:79], v[18:33]
	v_mfma_f32_32x32x16_bf16 v[2:17], v[72:75], v[76:79], v[2:17]
	v_mfma_f32_32x32x16_bf16 v[18:33], v[44:47], v[80:83], v[18:33]
	v_mfma_f32_32x32x16_bf16 v[2:17], v[48:51], v[80:83], v[2:17]
	v_mfma_f32_32x32x16_bf16 v[18:33], v[52:55], v[84:87], v[18:33]
	v_mfma_f32_32x32x16_bf16 v[2:17], v[56:59], v[84:87], v[2:17]
	v_mfma_f32_32x32x16_bf16 v[18:33], v[60:63], v[88:91], v[18:33]
	v_mfma_f32_32x32x16_bf16 v[2:17], v[64:67], v[88:91], v[2:17]
	s_cbranch_scc1 .LBB0_616
	v_cmp_gt_i32_e64 s[60:61], 26, v196
	v_cmp_gt_i32_e64 s[62:63], 27, v196
	v_cmp_gt_i32_e64 s[58:59], 25, v196
	s_and_b64 s[60:61], s[62:63], s[60:61]
	v_cmp_gt_i32_e64 s[56:57], 24, v196
	s_and_b64 s[58:59], s[60:61], s[58:59]
	v_cmp_gt_i32_e64 s[54:55], 19, v196
	s_and_b64 s[56:57], s[58:59], s[56:57]
	v_cmp_gt_i32_e64 s[52:53], 18, v196
	s_and_b64 s[54:55], s[56:57], s[54:55]
	v_cmp_gt_i32_e64 s[50:51], 17, v196
	s_and_b64 s[52:53], s[54:55], s[52:53]
	v_cmp_gt_i32_e64 s[48:49], 16, v196
	s_and_b64 s[50:51], s[52:53], s[50:51]
	v_cmp_gt_i32_e64 s[46:47], 11, v196
	s_and_b64 s[48:49], s[50:51], s[48:49]
	v_cmp_gt_i32_e64 s[44:45], 10, v196
	s_and_b64 s[46:47], s[48:49], s[46:47]
	v_cmp_gt_i32_e64 s[42:43], 9, v196
	s_and_b64 s[44:45], s[46:47], s[44:45]
	v_cmp_gt_i32_e64 s[40:41], 8, v196
	s_and_b64 s[42:43], s[44:45], s[42:43]
	v_cmp_gt_i32_e64 s[38:39], 3, v196
	s_and_b64 s[40:41], s[42:43], s[40:41]
	v_cmp_gt_i32_e64 s[36:37], 2, v196
	s_and_b64 s[38:39], s[40:41], s[38:39]
	v_cmp_gt_i32_e64 s[34:35], 1, v196
	s_and_b64 s[36:37], s[38:39], s[36:37]
	v_cmp_gt_i32_e64 s[30:31], 0, v196
	s_and_b64 s[34:35], s[36:37], s[34:35]
	s_and_b64 s[30:31], s[34:35], s[30:31]
	v_cmp_gt_i32_e64 s[28:29], 58, v196
	v_cndmask_b32_e64 v18, v18, v237, s[30:31]
	v_cmp_gt_i32_e64 s[30:31], 59, v196
	v_cmp_gt_i32_e64 s[26:27], 57, v196
	s_and_b64 s[28:29], s[30:31], s[28:29]
	v_cmp_gt_i32_e64 s[24:25], 56, v196
	s_and_b64 s[26:27], s[28:29], s[26:27]
	v_cmp_gt_i32_e64 s[22:23], 51, v196
	s_and_b64 s[24:25], s[26:27], s[24:25]
	v_cmp_gt_i32_e64 s[20:21], 50, v196
	s_and_b64 s[22:23], s[24:25], s[22:23]
	v_cmp_gt_i32_e64 s[18:19], 49, v196
	s_and_b64 s[20:21], s[22:23], s[20:21]
	v_cmp_gt_i32_e64 s[16:17], 48, v196
	s_and_b64 s[18:19], s[20:21], s[18:19]
	v_cmp_gt_i32_e64 s[14:15], 43, v196
	s_and_b64 s[16:17], s[18:19], s[16:17]
	v_cmp_gt_i32_e64 s[12:13], 42, v196
	s_and_b64 s[14:15], s[16:17], s[14:15]
	v_cmp_gt_i32_e64 s[10:11], 41, v196
	s_and_b64 s[12:13], s[14:15], s[12:13]
	v_cmp_gt_i32_e64 s[8:9], 40, v196
	s_and_b64 s[10:11], s[12:13], s[10:11]
	v_cmp_gt_i32_e64 s[6:7], 35, v196
	s_and_b64 s[8:9], s[10:11], s[8:9]
	v_cmp_gt_i32_e64 s[4:5], 34, v196
	s_and_b64 s[6:7], s[8:9], s[6:7]
	v_cmp_gt_i32_e64 s[2:3], 33, v196
	s_and_b64 s[4:5], s[6:7], s[4:5]
	v_cmp_gt_i32_e32 vcc, 32, v196
	s_and_b64 s[2:3], s[4:5], s[2:3]
	s_and_b64 vcc, s[2:3], vcc
	v_cndmask_b32_e64 v33, v33, v237, s[62:63]
	v_cndmask_b32_e64 v32, v32, v237, s[60:61]
	v_cndmask_b32_e64 v31, v31, v237, s[58:59]
	v_cndmask_b32_e64 v30, v30, v237, s[56:57]
	v_cndmask_b32_e64 v29, v29, v237, s[54:55]
	v_cndmask_b32_e64 v28, v28, v237, s[52:53]
	v_cndmask_b32_e64 v27, v27, v237, s[50:51]
	v_cndmask_b32_e64 v26, v26, v237, s[48:49]
	v_cndmask_b32_e64 v25, v25, v237, s[46:47]
	v_cndmask_b32_e64 v24, v24, v237, s[44:45]
	v_cndmask_b32_e64 v23, v23, v237, s[42:43]
	v_cndmask_b32_e64 v22, v22, v237, s[40:41]
	v_cndmask_b32_e64 v21, v21, v237, s[38:39]
	v_cndmask_b32_e64 v20, v20, v237, s[36:37]
	v_cndmask_b32_e64 v19, v19, v237, s[34:35]
	v_cndmask_b32_e64 v17, v17, v237, s[30:31]
	v_cndmask_b32_e64 v16, v16, v237, s[28:29]
	v_cndmask_b32_e64 v15, v15, v237, s[26:27]
	v_cndmask_b32_e64 v14, v14, v237, s[24:25]
	v_cndmask_b32_e64 v13, v13, v237, s[22:23]
	v_cndmask_b32_e64 v12, v12, v237, s[20:21]
	v_cndmask_b32_e64 v11, v11, v237, s[18:19]
	v_cndmask_b32_e64 v10, v10, v237, s[16:17]
	v_cndmask_b32_e64 v9, v9, v237, s[14:15]
	v_cndmask_b32_e64 v8, v8, v237, s[12:13]
	v_cndmask_b32_e64 v7, v7, v237, s[10:11]
	v_cndmask_b32_e64 v6, v6, v237, s[8:9]
	v_cndmask_b32_e64 v5, v5, v237, s[6:7]
	v_cndmask_b32_e64 v4, v4, v237, s[4:5]
	v_cndmask_b32_e64 v3, v3, v237, s[2:3]
	v_cndmask_b32_e32 v2, v2, v237, vcc

.LBB0_796:
	s_and_b64 vcc, exec, s[2:3]
	s_cbranch_vccz .LBB0_612
	s_ashr_i32 s75, s74, 31
	s_lshl_b64 s[66:67], s[74:75], 12
	v_readlane_b32 s0, v252, 28
	v_readlane_b32 s2, v252, 13
	v_mbcnt_lo_u32_b32 v147, -1, 0
	v_mbcnt_hi_u32_b32 v147, -1, v147
	s_add_u32 s0, s0, s66
	v_and_b32_e32 v150, 31, v147
	v_readlane_b32 s1, v252, 31
	v_readlane_b32 s3, v252, 14
	s_addc_u32 s1, s1, s67
	v_or_b32_e32 v0, s2, v150
	s_lshl_b64 s[2:3], s[74:75], 11
	v_readlane_b32 s4, v252, 34
	s_add_u32 s4, s4, s2
	v_readlane_b32 s5, v252, 37
	v_bfe_u32 v149, v147, 5, 1
	v_lshlrev_b64 v[8:9], 11, v[0:1]
	s_addc_u32 s5, s5, s3
	v_lshlrev_b32_e32 v2, 4, v149
	v_mov_b32_e32 v3, v1
	v_lshl_add_u64 v[4:5], s[4:5], 0, v[8:9]
	v_lshl_add_u64 v[4:5], v[4:5], 0, v[2:3]
	flat_load_dwordx4 v[40:43], v[4:5]
	v_lshlrev_b64 v[10:11], 12, v[0:1]
	v_lshl_add_u64 v[10:11], s[0:1], 0, v[10:11]
	v_readlane_b32 s0, v252, 40
	s_add_u32 s0, s0, s2
	v_readlane_b32 s1, v252, 43
	s_addc_u32 s1, s1, s3
	v_and_b32_e32 v148, 63, v147
	v_lshl_add_u64 v[8:9], s[0:1], 0, v[8:9]
	v_lshlrev_b32_e32 v34, 4, v148
	v_lshl_add_u64 v[8:9], v[8:9], 0, v[2:3]
	s_mov_b32 s0, 0x29900000
	v_add_u32_e32 v146, s70, v34
	v_lshl_add_u64 v[10:11], v[10:11], 0, v[2:3]
	v_add_co_u32_e32 v8, vcc, s0, v8
	flat_load_dwordx4 v[142:145], v[10:11]
	flat_load_dwordx4 v[138:141], v[10:11] offset:32
	flat_load_dwordx4 v[134:137], v[10:11] offset:64
	flat_load_dwordx4 v[130:133], v[10:11] offset:96
	flat_load_dwordx4 v[126:129], v[10:11] offset:128
	flat_load_dwordx4 v[122:125], v[10:11] offset:160
	flat_load_dwordx4 v[118:121], v[10:11] offset:192
	flat_load_dwordx4 v[114:117], v[10:11] offset:224
	v_addc_co_u32_e32 v9, vcc, 0, v9, vcc
	v_readlane_b32 s0, v251, 49
	flat_load_dwordx4 v[20:23], v[8:9] offset:32
	flat_load_dwordx4 v[24:27], v[8:9] offset:64
	flat_load_dwordx4 v[44:47], v[8:9] offset:96
	v_mov_b32_e32 v0, s0
	v_readlane_b32 s0, v252, 17
	v_or_b32_e32 v3, s0, v34
	s_mov_b32 s0, 0x51eb851f
	v_mul_hi_u32 v4, v3, s0
	v_or_b32_e32 v5, 0x2000, v3
	v_or_b32_e32 v6, 0x4000, v3
	v_lshrrev_b32_e32 v4, 7, v4
	v_mul_hi_u32 v12, v5, s0
	v_or_b32_e32 v7, 0x6000, v3
	v_mul_hi_u32 v13, v6, s0
	v_mul_u32_u24_e32 v15, 0x190, v4
	v_lshrrev_b32_e32 v12, 7, v12
	v_mul_hi_u32 v14, v7, s0
	v_lshrrev_b32_e32 v13, 7, v13
	v_sub_u32_e32 v3, v3, v15
	v_mul_u32_u24_e32 v15, 0x190, v12
	s_movk_i32 s0, 0x180
	v_mul_u32_u24_e32 v16, 0x190, v13
	v_lshrrev_b32_e32 v18, 4, v3
	v_sub_u32_e32 v5, v5, v15
	v_cmp_gt_u32_e32 vcc, s0, v3
	v_lshrrev_b32_e32 v14, 7, v14
	v_sub_u32_e32 v6, v6, v16
	v_cndmask_b32_e32 v3, 0, v18, vcc
	v_lshrrev_b32_e32 v15, 4, v5
	v_cmp_gt_u32_e32 vcc, s0, v5
	v_mul_u32_u24_e32 v17, 0x190, v14
	v_lshrrev_b32_e32 v16, 4, v6
	v_cmp_lt_u32_e64 s[4:5], 15, v3
	v_cndmask_b32_e32 v5, 0, v15, vcc
	v_cmp_gt_u32_e32 vcc, s0, v6
	v_sub_u32_e32 v7, v7, v17
	v_cndmask_b32_e64 v6, v0, v181, s[4:5]
	v_cndmask_b32_e32 v15, 0, v16, vcc
	v_cmp_lt_u32_e64 s[6:7], 15, v5
	v_or_b32_e32 v4, s78, v4
	v_lshrrev_b32_e32 v17, 4, v7
	v_cndmask_b32_e64 v158, 12, 7, s[4:5]
	v_cmp_gt_u32_e32 vcc, s0, v7
	v_cmp_lt_u32_e64 s[8:9], 15, v15
	v_lshl_add_u32 v162, v3, 4, v6
	v_cndmask_b32_e64 v3, v0, v181, s[6:7]
	v_and_or_b32 v12, v12, 63, s78
	v_cndmask_b32_e32 v7, 0, v17, vcc
	v_cndmask_b32_e64 v159, 12, 7, s[6:7]
	v_cndmask_b32_e64 v16, v0, v181, s[8:9]
	v_lshl_add_u32 v6, v4, v158, v162
	v_lshl_add_u32 v163, v5, 4, v3
	v_readlane_b32 s0, v250, 45
	v_and_or_b32 v13, v13, 63, s78
	v_cndmask_b32_e64 v160, 12, 7, s[8:9]
	v_cmp_lt_u32_e64 s[2:3], 15, v7
	v_lshl_add_u32 v164, v15, 4, v16
	v_lshl_add_u32 v5, v12, v159, v163
	v_cndmask_b32_e64 v0, v0, v181, s[2:3]
	v_lshl_add_u32 v4, v13, v160, v164
	v_and_or_b32 v14, v14, 63, s78
	v_cndmask_b32_e64 v161, 12, 7, s[2:3]
	v_lshl_add_u32 v165, v7, 4, v0
	v_lshl_add_u32 v3, v14, v161, v165
	s_mov_b32 m0, s0
	s_nop 0
	global_load_lds_dwordx4 v6, s[68:69]
	v_readlane_b32 s0, v251, 43
	s_mov_b32 m0, s0
	s_nop 0
	global_load_lds_dwordx4 v5, s[68:69]
	v_readlane_b32 s0, v251, 1
	s_mov_b32 m0, s33
	s_nop 0
	global_load_lds_dwordx4 v4, s[68:69]
	v_readlane_b32 s1, v251, 2
	s_and_b64 vcc, exec, s[0:1]
	s_cbranch_vccnz .LBB0_799
	s_cmp_lg_u32 0, -1
	s_cselect_b32 s0, 0, 0
	s_add_i32 s0, s0, 0x12000
	s_mov_b32 m0, s0
	s_nop 0
	global_load_lds_dwordx4 v3, s[68:69]
.LBB0_799:
	v_readlane_b32 s0, v250, 63
	v_lshlrev_b32_e32 v38, 3, v148
	v_and_b32_e32 v35, 32, v147
	v_add_u32_e32 v7, s0, v147
	v_bfe_u32 v0, v7, 2, 2
	v_lshrrev_b32_e32 v7, 1, v7
	v_and_b32_e32 v37, 8, v7
	v_readlane_b32 s0, v252, 3
	v_and_b32_e32 v36, 24, v38
	v_cndmask_b32_e64 v8, v248, v236, s[4:5]
	v_or3_b32 v7, v0, s0, v37
	v_lshl_or_b32 v7, v7, 11, v35
	v_or3_b32 v7, v7, s72, v36
	v_lshlrev_b32_e32 v7, 1, v7
	v_add_u32_e32 v11, 0x1f700000, v7
	s_mov_b32 m0, s85
	s_nop 0
	global_load_lds_dwordx4 v11, s[68:69]
	v_readlane_b32 s0, v253, 4
	v_add_u32_e32 v12, 0x1f700080, v7
	s_mov_b32 m0, s0
	s_nop 0
	global_load_lds_dwordx4 v12, s[68:69]
	v_readlane_b32 s0, v251, 45
	v_cndmask_b32_e64 v9, v248, v236, s[6:7]
	s_waitcnt vmcnt(0) lgkmcnt(0)
	ds_write_b128 v146, v[40:43]
	ds_write_b128 v146, v[20:23] offset:1024
	ds_write_b128 v146, v[24:27] offset:2048
	ds_write_b128 v146, v[44:47] offset:3072
	s_waitcnt vmcnt(2)
	s_waitcnt lgkmcnt(0)
	s_barrier
	v_add_u32_e32 v6, v6, v8
	s_mov_b32 m0, s0
	s_nop 0
	global_load_lds_dwordx4 v6, s[68:69]
	v_readlane_b32 s0, v252, 9
	v_add_u32_e32 v5, v5, v9
	s_mov_b32 m0, s0
	s_nop 0
	global_load_lds_dwordx4 v5, s[68:69]
	v_readlane_b32 s0, v251, 1
	v_cndmask_b32_e64 v10, v248, v236, s[8:9]
	v_readlane_b32 s1, v251, 2
	v_add_u32_e32 v4, v4, v10
	s_and_b64 vcc, exec, s[0:1]
	v_readlane_b32 s0, v251, 47
	s_mov_b32 m0, s0
	s_nop 0
	global_load_lds_dwordx4 v4, s[68:69]
	s_cbranch_vccnz .LBB0_801
	s_cmp_lg_u32 0, -1
	v_cndmask_b32_e64 v4, v248, v236, s[2:3]
	s_cselect_b32 s0, 0, 0
	v_add_u32_e32 v3, v3, v4
	s_add_i32 s0, s0, 0x18400
	s_mov_b32 m0, s0
	s_nop 0
	global_load_lds_dwordx4 v3, s[68:69]
